# cand18 + item pipeline: waits on an item's row loads moved ahead of the other item's loads so they no longer wait for the just-issued stores/atomics
# baseline (speedup 1.0000x reference)
.LBB0_43:
	s_lshr_b32 s48, s34, 6
	v_cvt_f32_u32_e32 v1, s48
	s_sub_i32 s49, 0, s48
	s_abs_i32 s47, s73
	s_ashr_i32 s46, s73, 31
	v_rcp_iflag_f32_e32 v1, v1
	v_mov_b32_e32 v141, 0
	s_mov_b32 s35, 0
	v_lshlrev_b32_e32 v138, 2, v194
	v_mul_f32_e32 v1, 0x4f7ffffe, v1
	v_cvt_u32_f32_e32 v1, v1
	v_mov_b32_e32 v139, v141
	v_mov_b32_e32 v3, v2
	v_lshlrev_b32_e32 v140, 1, v193
	v_readfirstlane_b32 s50, v1
	s_mul_i32 s49, s49, s50
	s_mul_hi_u32 s49, s50, s49
	s_add_i32 s50, s50, s49
	s_mul_hi_u32 s49, s47, s50
	s_mul_i32 s50, s49, s48
	s_sub_i32 s47, s47, s50
	s_add_i32 s51, s49, 1
	s_sub_i32 s50, s47, s48
	s_cmp_ge_u32 s47, s48
	s_cselect_b32 s49, s51, s49
	s_cselect_b32 s47, s50, s47
	s_add_i32 s50, s49, 1
	s_cmp_ge_u32 s47, s48
	s_cselect_b32 s47, s50, s49
	s_xor_b32 s47, s47, s46
	s_sub_i32 s49, s47, s46
	s_lshl_b32 s46, s49, 6
	v_or_b32_e32 v1, s46, v137
	s_ashr_i32 s46, s46, 31
	s_mul_i32 s50, s46, s34
	v_mad_u64_u32 v[4:5], s[46:47], v1, s34, 0
	v_add_u32_e32 v5, s50, v5
	s_mul_i32 s49, s49, s48
	s_waitcnt lgkmcnt(0)
	v_lshl_add_u64 v[4:5], v[4:5], 2, s[2:3]
	s_sub_i32 s2, s73, s49
	s_lshl_b32 s2, s2, 6
	s_ashr_i32 s3, s2, 31
	v_lshl_add_u64 v[4:5], s[2:3], 2, v[4:5]
	v_lshl_add_u64 v[4:5], v[4:5], 0, v[138:139]
	s_lshl_b64 s[2:3], s[34:35], 4
	v_lshl_add_u64 v[14:15], v[4:5], 0, s[2:3]
	global_load_dwordx4 v[6:9], v[4:5], off nt
	global_load_dwordx4 v[10:13], v[14:15], off nt
	v_lshl_add_u64 v[4:5], v[14:15], 0, s[2:3]
	v_lshl_add_u64 v[22:23], v[4:5], 0, s[2:3]
	global_load_dwordx4 v[14:17], v[4:5], off nt
	global_load_dwordx4 v[18:21], v[22:23], off nt
	v_lshl_add_u64 v[4:5], v[22:23], 0, s[2:3]
	v_lshl_add_u64 v[30:31], v[4:5], 0, s[2:3]
	global_load_dwordx4 v[22:25], v[4:5], off nt
	global_load_dwordx4 v[26:29], v[30:31], off nt
	v_lshl_add_u64 v[4:5], v[30:31], 0, s[2:3]
	v_lshl_add_u64 v[38:39], v[4:5], 0, s[2:3]
	global_load_dwordx4 v[30:33], v[4:5], off nt
	global_load_dwordx4 v[34:37], v[38:39], off nt
	v_lshl_add_u64 v[4:5], v[38:39], 0, s[2:3]
	global_load_dwordx4 v[38:41], v[4:5], off nt
	v_lshl_add_u64 v[4:5], v[4:5], 0, s[2:3]
	global_load_dwordx4 v[46:49], v[4:5], off nt
	v_lshl_add_u64 v[4:5], v[4:5], 0, s[2:3]
	global_load_dwordx4 v[50:53], v[4:5], off nt
	v_lshl_add_u64 v[4:5], v[4:5], 0, s[2:3]
	global_load_dwordx4 v[62:65], v[4:5], off nt
	v_lshl_add_u64 v[4:5], v[4:5], 0, s[2:3]
	global_load_dwordx4 v[66:69], v[4:5], off nt
	v_lshl_add_u64 v[4:5], v[4:5], 0, s[2:3]
	global_load_dwordx4 v[82:85], v[4:5], off nt
	v_lshl_add_u64 v[4:5], v[4:5], 0, s[2:3]
	global_load_dwordx4 v[90:93], v[4:5], off nt
	v_lshl_add_u64 v[4:5], v[4:5], 0, s[2:3]
	global_load_dwordx4 v[102:105], v[4:5], off nt
	v_mov_b32_e32 v5, v136
	v_mov_b32_e32 v1, v2
	v_mov_b32_e32 v4, v2
	s_mov_b32 s46, 0x3e000000
	v_mbcnt_hi_u32_b32 v195, -1, v234
	s_mov_b32 s55, s14
	s_mov_b32 s54, s34
	s_mov_b32 s84, 0
	s_branch .LBB0_47

.LBB0_63:
	s_lshr_b32 s60, s34, 6
	v_cvt_f32_u32_e32 v42, s60
	s_sub_i32 s63, 0, s60
	s_abs_i32 s62, s47
	s_ashr_i32 s61, s47, 31
	v_rcp_iflag_f32_e32 v42, v42
	v_mov_b32_e32 v139, v141
	v_mul_f32_e32 v42, 0x4f7ffffe, v42
	v_cvt_u32_f32_e32 v42, v42
	s_nop 0
	v_readfirstlane_b32 s76, v42
	s_mul_i32 s63, s63, s76
	s_mul_hi_u32 s63, s76, s63
	s_add_i32 s76, s76, s63
	s_mul_hi_u32 s63, s62, s76
	s_mul_i32 s76, s63, s60
	s_sub_i32 s62, s62, s76
	s_add_i32 s77, s63, 1
	s_sub_i32 s76, s62, s60
	s_cmp_ge_u32 s62, s60
	s_cselect_b32 s63, s77, s63
	s_cselect_b32 s62, s76, s62
	s_add_i32 s76, s63, 1
	s_cmp_ge_u32 s62, s60
	s_cselect_b32 s62, s76, s63
	s_xor_b32 s62, s62, s61
	s_sub_i32 s61, s62, s61
	s_mul_i32 s60, s61, s60
	s_lshl_b32 s61, s61, 6
	s_sub_i32 s62, s47, s60
	v_or_b32_e32 v42, s61, v137
	s_ashr_i32 s60, s61, 31
	s_mul_i32 s63, s60, s34
	v_mad_u64_u32 v[42:43], s[60:61], v42, s34, 0
	v_add_u32_e32 v43, s63, v43
	s_waitcnt lgkmcnt(0)
	v_lshl_add_u64 v[42:43], v[42:43], 2, s[2:3]
	s_lshl_b32 s2, s62, 6
	s_ashr_i32 s3, s2, 31
	v_lshl_add_u64 v[42:43], s[2:3], 2, v[42:43]
	v_lshl_add_u64 v[42:43], v[42:43], 0, v[138:139]
	s_lshl_b64 s[2:3], s[34:35], 4
	v_lshl_add_u64 v[58:59], v[42:43], 0, s[2:3]
	s_cmp_eq_u32 s84, 0
	s_cbranch_scc1 .Lp0e_tb_done
	s_cmp_eq_u32 s84, 1
	s_cbranch_scc1 .Lp0e_tb8
	s_waitcnt vmcnt(12)
	s_branch .Lp0e_tb_done
.Lp0e_tb8:
	s_waitcnt vmcnt(8)
.Lp0e_tb_done:
	global_load_dwordx4 v[42:45], v[42:43], off nt
	s_nop 0
	global_load_dwordx4 v[54:57], v[58:59], off nt
	v_lshl_add_u64 v[58:59], v[58:59], 0, s[2:3]
	v_lshl_add_u64 v[74:75], v[58:59], 0, s[2:3]
	global_load_dwordx4 v[58:61], v[58:59], off nt
	s_nop 0
	global_load_dwordx4 v[70:73], v[74:75], off nt
	v_lshl_add_u64 v[74:75], v[74:75], 0, s[2:3]
	v_lshl_add_u64 v[86:87], v[74:75], 0, s[2:3]
	global_load_dwordx4 v[74:77], v[74:75], off nt
	s_nop 0
	global_load_dwordx4 v[78:81], v[86:87], off nt
	v_lshl_add_u64 v[86:87], v[86:87], 0, s[2:3]
	v_lshl_add_u64 v[98:99], v[86:87], 0, s[2:3]
	v_lshl_add_u64 v[106:107], v[98:99], 0, s[2:3]
	v_lshl_add_u64 v[110:111], v[106:107], 0, s[2:3]
	v_lshl_add_u64 v[114:115], v[110:111], 0, s[2:3]
	v_lshl_add_u64 v[118:119], v[114:115], 0, s[2:3]
	v_lshl_add_u64 v[122:123], v[118:119], 0, s[2:3]
	v_lshl_add_u64 v[126:127], v[122:123], 0, s[2:3]
	v_lshl_add_u64 v[130:131], v[126:127], 0, s[2:3]
	global_load_dwordx4 v[86:89], v[86:87], off nt
	s_nop 0
	global_load_dwordx4 v[94:97], v[98:99], off nt
	s_nop 0
	global_load_dwordx4 v[98:101], v[106:107], off nt
	s_nop 0
	global_load_dwordx4 v[106:109], v[110:111], off nt
	s_nop 0
	global_load_dwordx4 v[110:113], v[114:115], off nt
	s_nop 0
	global_load_dwordx4 v[114:117], v[118:119], off nt
	s_nop 0
	global_load_dwordx4 v[118:121], v[122:123], off nt
	s_nop 0
	global_load_dwordx4 v[122:125], v[126:127], off nt
	s_nop 0
	global_load_dwordx4 v[126:129], v[130:131], off nt
	v_lshl_add_u64 v[130:131], v[130:131], 0, s[2:3]
	global_load_dwordx4 v[130:133], v[130:131], off nt
.LBB0_64:
	s_andn2_b64 vcc, exec, s[30:31]
	s_cbranch_vccnz .LBB0_66
	s_cmp_lg_u64 s[58:59], 0
	s_cbranch_scc0 .Lp0i_lad0
	s_cmp_lg_u32 s84, 0
	s_cbranch_scc1 .Lp0i_lad1
	s_waitcnt vmcnt(16)
	s_branch .Lp0i_lad1

.Lp0i_nog_A:
	s_cmp_lg_u64 s[58:59], 0
	s_cbranch_scc0 .Lp0i_w0_A
	s_cmp_lg_u32 s84, 0
	s_cbranch_scc1 .LBB0_68
	s_waitcnt vmcnt(16)
	s_branch .LBB0_68

.LBB0_98:
	s_mul_i32 s76, s76, s61
	s_sub_i32 s2, s73, s76
	s_lshl_b32 s2, s2, 6
	v_mul_f32_e32 v144, v102, v139
	v_mul_f32_e32 v145, v103, v139
	v_cvt_pk_bf16_f32 v144, v144, v145
	v_mul_f32_e32 v145, v104, v139
	s_cmp_eq_u64 s[38:39], 0
	v_mul_f32_e32 v139, v105, v139
	v_cvt_pk_bf16_f32 v145, v145, v139
	ds_write_b64 v196, v[144:145] offset:8640
	s_cselect_b32 s83, 0, 1
	s_cbranch_scc1 .LBB0_102
	v_lshlrev_b32_e32 v139, 16, v142
	v_and_b32_e32 v142, 0xffff0000, v142
	v_lshlrev_b32_e32 v198, 16, v146
	v_and_b32_e32 v146, 0xffff0000, v146
	v_lshlrev_b32_e32 v197, 16, v143
	v_and_b32_e32 v143, 0xffff0000, v143
	v_max3_f32 v142, |v142|, 0, |v146|
	v_lshlrev_b32_e32 v146, 16, v147
	v_and_b32_e32 v147, 0xffff0000, v147
	v_max3_f32 v139, |v139|, 0, |v198|
	v_max3_f32 v143, |v143|, 0, |v147|
	v_lshlrev_b32_e32 v147, 16, v148
	v_lshlrev_b32_e32 v198, 16, v150
	v_and_b32_e32 v148, 0xffff0000, v148
	v_max3_f32 v139, v139, |v147|, |v198|
	v_and_b32_e32 v147, 0xffff0000, v150
	v_max3_f32 v146, |v197|, 0, |v146|
	v_lshlrev_b32_e32 v197, 16, v149
	v_max3_f32 v142, v142, |v148|, |v147|
	v_lshlrev_b32_e32 v147, 16, v151
	v_and_b32_e32 v149, 0xffff0000, v149
	v_max3_f32 v146, v146, |v197|, |v147|
	v_and_b32_e32 v147, 0xffff0000, v151
	v_max3_f32 v143, v143, |v149|, |v147|
	v_lshlrev_b32_e32 v147, 16, v152
	v_lshlrev_b32_e32 v151, 16, v154
	v_and_b32_e32 v148, 0xffff0000, v152
	v_max3_f32 v139, v139, |v147|, |v151|
	v_and_b32_e32 v147, 0xffff0000, v154
	v_lshlrev_b32_e32 v149, 16, v153
	v_max3_f32 v142, v142, |v148|, |v147|
	v_lshlrev_b32_e32 v147, 16, v155
	v_and_b32_e32 v150, 0xffff0000, v153
	v_max3_f32 v146, v146, |v149|, |v147|
	v_and_b32_e32 v147, 0xffff0000, v155
	v_max3_f32 v143, v143, |v150|, |v147|
	v_lshlrev_b32_e32 v147, 16, v156
	v_lshlrev_b32_e32 v151, 16, v158
	v_and_b32_e32 v148, 0xffff0000, v156
	v_max3_f32 v139, v139, |v147|, |v151|
	v_and_b32_e32 v147, 0xffff0000, v158
	v_lshlrev_b32_e32 v149, 16, v157
	v_max3_f32 v142, v142, |v148|, |v147|
	v_lshlrev_b32_e32 v147, 16, v159
	v_and_b32_e32 v150, 0xffff0000, v157
	v_max3_f32 v146, v146, |v149|, |v147|
	v_and_b32_e32 v147, 0xffff0000, v159
	v_max3_f32 v143, v143, |v150|, |v147|
	v_lshlrev_b32_e32 v147, 16, v160
	v_lshlrev_b32_e32 v151, 16, v162
	v_and_b32_e32 v148, 0xffff0000, v160
	v_max3_f32 v139, v139, |v147|, |v151|
	v_and_b32_e32 v147, 0xffff0000, v162
	v_lshlrev_b32_e32 v149, 16, v161
	v_max3_f32 v142, v142, |v148|, |v147|
	v_lshlrev_b32_e32 v147, 16, v163
	v_and_b32_e32 v150, 0xffff0000, v161
	v_max3_f32 v146, v146, |v149|, |v147|
	v_and_b32_e32 v147, 0xffff0000, v163
	v_max3_f32 v143, v143, |v150|, |v147|
	v_lshlrev_b32_e32 v147, 16, v164
	v_lshlrev_b32_e32 v151, 16, v166
	v_and_b32_e32 v148, 0xffff0000, v164
	v_max3_f32 v139, v139, |v147|, |v151|
	v_and_b32_e32 v147, 0xffff0000, v166
	v_lshlrev_b32_e32 v149, 16, v165
	v_max3_f32 v142, v142, |v148|, |v147|
	v_lshlrev_b32_e32 v147, 16, v167
	v_and_b32_e32 v150, 0xffff0000, v165
	v_max3_f32 v146, v146, |v149|, |v147|
	v_and_b32_e32 v147, 0xffff0000, v167
	v_max3_f32 v143, v143, |v150|, |v147|
	v_lshlrev_b32_e32 v147, 16, v168
	v_lshlrev_b32_e32 v151, 16, v170
	v_and_b32_e32 v148, 0xffff0000, v168
	v_max3_f32 v139, v139, |v147|, |v151|
	v_and_b32_e32 v147, 0xffff0000, v170
	v_lshlrev_b32_e32 v149, 16, v169
	v_max3_f32 v142, v142, |v148|, |v147|
	v_lshlrev_b32_e32 v147, 16, v171
	v_and_b32_e32 v150, 0xffff0000, v169
	v_max3_f32 v146, v146, |v149|, |v147|
	v_and_b32_e32 v147, 0xffff0000, v171
	v_max3_f32 v143, v143, |v150|, |v147|
	v_and_b32_e32 v150, 0xffff0000, v173
	v_and_b32_e32 v151, 0xffff0000, v145
	v_lshlrev_b32_e32 v147, 16, v172
	v_max3_f32 v150, v143, |v150|, |v151|
	v_lshlrev_b32_e32 v143, 16, v144
	v_max3_f32 v139, v139, |v147|, |v143|
	v_and_b32_e32 v147, 64, v195
	v_xor_b32_e32 v143, 16, v195
	v_add_u32_e32 v147, 64, v147
	v_cmp_lt_i32_e32 vcc, v143, v147
	v_and_b32_e32 v148, 0xffff0000, v172
	v_and_b32_e32 v144, 0xffff0000, v144
	v_cndmask_b32_e32 v143, v195, v143, vcc
	v_lshlrev_b32_e32 v151, 2, v143
	ds_bpermute_b32 v143, v151, v139
	v_lshlrev_b32_e32 v149, 16, v173
	v_lshlrev_b32_e32 v145, 16, v145
	v_max3_f32 v144, v142, |v148|, |v144|
	v_max3_f32 v145, v146, |v149|, |v145|
	s_waitcnt lgkmcnt(0)
	v_max_f32_e32 v142, v143, v143
	v_max_f32_e32 v139, v139, v142
	v_xor_b32_e32 v142, 32, v195
	ds_bpermute_b32 v143, v151, v144
	v_cmp_lt_i32_e32 vcc, v142, v147
	ds_bpermute_b32 v146, v151, v145
	ds_bpermute_b32 v147, v151, v150
	v_cndmask_b32_e32 v142, v195, v142, vcc
	s_waitcnt lgkmcnt(2)
	v_max_f32_e32 v143, v143, v143
	v_lshlrev_b32_e32 v148, 2, v142
	s_waitcnt lgkmcnt(1)
	v_max_f32_e32 v146, v146, v146
	s_waitcnt lgkmcnt(0)
	v_max_f32_e32 v147, v147, v147
	v_max_f32_e32 v143, v144, v143
	v_max_f32_e32 v145, v145, v146
	v_max_f32_e32 v147, v150, v147
	ds_bpermute_b32 v142, v148, v139
	ds_bpermute_b32 v144, v148, v143
	ds_bpermute_b32 v146, v148, v145
	ds_bpermute_b32 v148, v148, v147
	s_and_saveexec_b64 s[62:63], s[0:1]
	s_cbranch_execz .LBB0_101
	s_ashr_i32 s3, s2, 31
	s_lshl_b64 s[76:77], s[2:3], 2
	s_waitcnt lgkmcnt(3)
	v_max_f32_e32 v142, v142, v142
	v_max_f32_e32 v139, v139, v139
	s_add_u32 s76, s38, s76
	s_waitcnt lgkmcnt(0)
	v_max_f32_e32 v148, v148, v148
	v_max_f32_e32 v147, v147, v147
	v_max_f32_e32 v146, v146, v146
	v_max_f32_e32 v145, v145, v145
	v_max_f32_e32 v144, v144, v144
	v_max_f32_e32 v143, v143, v143
	v_max_f32_e32 v139, v139, v142
	s_addc_u32 s77, s39, s77
	v_lshlrev_b32_e32 v142, 2, v174
	v_max_f32_e32 v147, v147, v148
	v_max_f32_e32 v145, v145, v146
	v_max_f32_e32 v143, v143, v144
	global_atomic_umax v142, v139, s[76:77]
	global_atomic_umax v142, v143, s[76:77] offset:4
	global_atomic_umax v142, v145, s[76:77] offset:8
	global_atomic_umax v142, v147, s[76:77] offset:12

.LBB0_102:
	s_waitcnt lgkmcnt(0)
	v_add_u32_e32 v201, v178, v177
	v_add_u32_e32 v200, v179, v177
	s_waitcnt lgkmcnt(3)
	ds_read_b64_tr_b16 v[142:143], v201
	s_waitcnt lgkmcnt(2)
	ds_read_b64_tr_b16 v[146:147], v201 offset:32
	ds_read_b64_tr_b16 v[150:151], v201 offset:64
	ds_read_b64_tr_b16 v[154:155], v201 offset:96
	ds_read_b64_tr_b16 v[144:145], v201 offset:576
	s_waitcnt lgkmcnt(5)
	ds_read_b64_tr_b16 v[148:149], v201 offset:608
	ds_read_b64_tr_b16 v[152:153], v201 offset:640
	ds_read_b64_tr_b16 v[156:157], v201 offset:672
	ds_read_b64_tr_b16 v[158:159], v200
	ds_read_b64_tr_b16 v[162:163], v200 offset:32
	ds_read_b64_tr_b16 v[166:167], v200 offset:64
	ds_read_b64_tr_b16 v[170:171], v200 offset:96
	ds_read_b64_tr_b16 v[160:161], v200 offset:576
	ds_read_b64_tr_b16 v[164:165], v200 offset:608
	ds_read_b64_tr_b16 v[168:169], v200 offset:640
	ds_read_b64_tr_b16 v[172:173], v200 offset:672
	v_add_u32_e32 v198, v180, v181
	v_add_u32_e32 v199, v180, v182
	s_waitcnt lgkmcnt(0)
	s_waitcnt lgkmcnt(11)
	ds_write_b128 v198, v[142:145]
	s_waitcnt lgkmcnt(4)
	ds_write_b128 v199, v[158:161]
	ds_write_b128 v198, v[146:149] offset:2304
	s_waitcnt lgkmcnt(5)
	ds_write_b128 v199, v[162:165] offset:2304
	ds_write_b128 v198, v[150:153] offset:4608
	s_waitcnt lgkmcnt(6)
	ds_write_b128 v199, v[166:169] offset:4608
	ds_write_b128 v198, v[154:157] offset:6912
	s_waitcnt lgkmcnt(7)
	ds_write_b128 v199, v[170:173] offset:6912
	s_waitcnt lgkmcnt(0)
	v_add_u32_e32 v197, v184, v185
	v_or_b32_e32 v139, s2, v183
	s_ashr_i32 s3, s2, 31
	ds_read_b128 v[142:145], v197
	s_mul_i32 s76, s3, s74
	v_mad_u64_u32 v[146:147], s[62:63], v139, s74, 0
	s_ashr_i32 s61, s60, 31
	v_add_u32_e32 v147, s76, v147
	v_lshl_add_u64 v[146:147], v[146:147], 1, s[36:37]
	s_lshl_b64 s[60:61], s[60:61], 1
	v_lshl_add_u64 v[146:147], v[146:147], 0, s[60:61]
	v_lshl_add_u64 v[150:151], v[146:147], 0, v[140:141]
	v_or_b32_e32 v139, s2, v186
	ds_read_b128 v[146:149], v197 offset:1152
	s_waitcnt lgkmcnt(1)
	global_store_dwordx4 v[150:151], v[142:145], off
	s_nop 1
	v_mad_u64_u32 v[142:143], s[62:63], v139, s74, 0
	v_add_u32_e32 v143, s76, v143
	v_lshl_add_u64 v[142:143], v[142:143], 1, s[36:37]
	v_lshl_add_u64 v[142:143], v[142:143], 0, s[60:61]
	v_lshl_add_u64 v[142:143], v[142:143], 0, v[140:141]
	v_or_b32_e32 v139, s2, v187
	s_waitcnt lgkmcnt(0)
	global_store_dwordx4 v[142:143], v[146:149], off
	ds_read_b128 v[142:145], v197 offset:2304
	s_nop 0
	v_mad_u64_u32 v[146:147], s[62:63], v139, s74, 0
	v_add_u32_e32 v147, s76, v147
	v_lshl_add_u64 v[146:147], v[146:147], 1, s[36:37]
	v_lshl_add_u64 v[146:147], v[146:147], 0, s[60:61]
	v_lshl_add_u64 v[150:151], v[146:147], 0, v[140:141]
	v_or_b32_e32 v139, s2, v188
	ds_read_b128 v[146:149], v197 offset:3456
	s_waitcnt lgkmcnt(1)
	global_store_dwordx4 v[150:151], v[142:145], off
	s_nop 1
	v_mad_u64_u32 v[142:143], s[62:63], v139, s74, 0
	v_add_u32_e32 v143, s76, v143
	v_lshl_add_u64 v[142:143], v[142:143], 1, s[36:37]
	v_lshl_add_u64 v[142:143], v[142:143], 0, s[60:61]
	v_lshl_add_u64 v[142:143], v[142:143], 0, v[140:141]
	v_or_b32_e32 v139, s2, v189
	s_waitcnt lgkmcnt(0)
	global_store_dwordx4 v[142:143], v[146:149], off
	ds_read_b128 v[142:145], v197 offset:4608
	s_nop 0
	v_mad_u64_u32 v[146:147], s[62:63], v139, s74, 0
	v_add_u32_e32 v147, s76, v147
	v_lshl_add_u64 v[146:147], v[146:147], 1, s[36:37]
	v_lshl_add_u64 v[146:147], v[146:147], 0, s[60:61]
	v_lshl_add_u64 v[150:151], v[146:147], 0, v[140:141]
	v_or_b32_e32 v139, s2, v190
	ds_read_b128 v[146:149], v197 offset:5760
	s_waitcnt lgkmcnt(1)
	global_store_dwordx4 v[150:151], v[142:145], off
	s_nop 1
	v_mad_u64_u32 v[142:143], s[62:63], v139, s74, 0
	v_add_u32_e32 v143, s76, v143
	v_lshl_add_u64 v[142:143], v[142:143], 1, s[36:37]
	v_lshl_add_u64 v[142:143], v[142:143], 0, s[60:61]
	v_lshl_add_u64 v[142:143], v[142:143], 0, v[140:141]
	v_or_b32_e32 v139, s2, v191
	s_waitcnt lgkmcnt(0)
	global_store_dwordx4 v[142:143], v[146:149], off
	ds_read_b128 v[142:145], v197 offset:6912
	s_nop 0
	v_mad_u64_u32 v[146:147], s[62:63], v139, s74, 0
	v_add_u32_e32 v147, s76, v147
	v_lshl_add_u64 v[146:147], v[146:147], 1, s[36:37]
	v_lshl_add_u64 v[146:147], v[146:147], 0, s[60:61]
	v_lshl_add_u64 v[150:151], v[146:147], 0, v[140:141]
	v_or_b32_e32 v139, s2, v192
	ds_read_b128 v[146:149], v197 offset:8064
	s_waitcnt lgkmcnt(1)
	global_store_dwordx4 v[150:151], v[142:145], off
	s_nop 1
	v_mad_u64_u32 v[142:143], s[2:3], v139, s74, 0
	v_add_u32_e32 v143, s76, v143
	v_lshl_add_u64 v[142:143], v[142:143], 1, s[36:37]
	v_lshl_add_u64 v[142:143], v[142:143], 0, s[60:61]
	v_lshl_add_u64 v[142:143], v[142:143], 0, v[140:141]
	s_waitcnt lgkmcnt(0)
	global_store_dwordx4 v[142:143], v[146:149], off
	s_add_i32 s76, s55, s40
	s_waitcnt lgkmcnt(0)
	s_cmp_ge_i32 s76, s72
	s_cselect_b64 s[60:61], -1, 0
	s_and_b64 vcc, exec, s[60:61]
	s_cbranch_vccz .LBB0_104
	s_andn2_b64 vcc, exec, s[58:59]
	s_cbranch_vccnz .LBB0_46
	s_waitcnt vmcnt(0)
	s_branch .LBB0_120

.LBB0_119:
	s_lshr_b32 s62, s54, 6
	v_cvt_f32_u32_e32 v6, s62
	s_sub_i32 s78, 0, s62
	s_abs_i32 s77, s73
	s_ashr_i32 s63, s73, 31
	v_rcp_iflag_f32_e32 v6, v6
	s_mov_b32 s55, s35
	v_mov_b32_e32 v139, v141
	v_mul_f32_e32 v6, 0x4f7ffffe, v6
	v_cvt_u32_f32_e32 v6, v6
	s_nop 0
	v_readfirstlane_b32 s79, v6
	s_mul_i32 s78, s78, s79
	s_mul_hi_u32 s78, s79, s78
	s_add_i32 s79, s79, s78
	s_mul_hi_u32 s78, s77, s79
	s_mul_i32 s79, s78, s62
	s_sub_i32 s77, s77, s79
	s_add_i32 s80, s78, 1
	s_sub_i32 s79, s77, s62
	s_cmp_ge_u32 s77, s62
	s_cselect_b32 s78, s80, s78
	s_cselect_b32 s77, s79, s77
	s_add_i32 s79, s78, 1
	s_cmp_ge_u32 s77, s62
	s_cselect_b32 s77, s79, s78
	s_xor_b32 s77, s77, s63
	s_sub_i32 s63, s77, s63
	s_mul_i32 s62, s63, s62
	s_lshl_b32 s63, s63, 6
	s_sub_i32 s77, s73, s62
	v_or_b32_e32 v6, s63, v137
	s_ashr_i32 s62, s63, 31
	s_mul_i32 s78, s62, s54
	v_mad_u64_u32 v[6:7], s[62:63], v6, s54, 0
	v_add_u32_e32 v7, s78, v7
	s_waitcnt lgkmcnt(0)
	v_lshl_add_u64 v[6:7], v[6:7], 2, s[2:3]
	s_lshl_b32 s2, s77, 6
	s_ashr_i32 s3, s2, 31
	v_lshl_add_u64 v[6:7], s[2:3], 2, v[6:7]
	v_lshl_add_u64 v[6:7], v[6:7], 0, v[138:139]
	s_lshl_b64 s[2:3], s[54:55], 4
	v_lshl_add_u64 v[14:15], v[6:7], 0, s[2:3]
	s_cmp_lg_u32 s83, 0
	s_cbranch_scc1 .Lp0e_xa12
	s_waitcnt vmcnt(8)
	s_branch .Lp0e_xa_done
.Lp0e_xa12:
	s_waitcnt vmcnt(12)
.Lp0e_xa_done:
	global_load_dwordx4 v[6:9], v[6:7], off nt
	s_nop 0
	global_load_dwordx4 v[10:13], v[14:15], off nt
	v_lshl_add_u64 v[14:15], v[14:15], 0, s[2:3]
	v_lshl_add_u64 v[22:23], v[14:15], 0, s[2:3]
	global_load_dwordx4 v[14:17], v[14:15], off nt
	s_nop 0
	global_load_dwordx4 v[18:21], v[22:23], off nt
	v_lshl_add_u64 v[22:23], v[22:23], 0, s[2:3]
	v_lshl_add_u64 v[30:31], v[22:23], 0, s[2:3]
	global_load_dwordx4 v[22:25], v[22:23], off nt
	s_nop 0
	global_load_dwordx4 v[26:29], v[30:31], off nt
	v_lshl_add_u64 v[30:31], v[30:31], 0, s[2:3]
	v_lshl_add_u64 v[38:39], v[30:31], 0, s[2:3]
	v_lshl_add_u64 v[46:47], v[38:39], 0, s[2:3]
	v_lshl_add_u64 v[50:51], v[46:47], 0, s[2:3]
	v_lshl_add_u64 v[62:63], v[50:51], 0, s[2:3]
	v_lshl_add_u64 v[66:67], v[62:63], 0, s[2:3]
	v_lshl_add_u64 v[82:83], v[66:67], 0, s[2:3]
	v_lshl_add_u64 v[90:91], v[82:83], 0, s[2:3]
	v_lshl_add_u64 v[102:103], v[90:91], 0, s[2:3]
	global_load_dwordx4 v[30:33], v[30:31], off nt
	s_nop 0
	global_load_dwordx4 v[34:37], v[38:39], off nt
	s_nop 0
	global_load_dwordx4 v[38:41], v[46:47], off nt
	s_nop 0
	global_load_dwordx4 v[46:49], v[50:51], off nt
	s_nop 0
	global_load_dwordx4 v[50:53], v[62:63], off nt
	s_nop 0
	global_load_dwordx4 v[62:65], v[66:67], off nt
	s_nop 0
	global_load_dwordx4 v[66:69], v[82:83], off nt
	s_nop 0
	global_load_dwordx4 v[82:85], v[90:91], off nt
	s_nop 0
	global_load_dwordx4 v[90:93], v[102:103], off nt
	v_lshl_add_u64 v[102:103], v[102:103], 0, s[2:3]
	global_load_dwordx4 v[102:105], v[102:103], off nt
	s_andn2_b64 vcc, exec, s[58:59]
	s_cbranch_vccnz .LBB0_46

.Lp0i_nog_B:
.LBB0_124:
	v_mul_f32_e32 v142, v42, v143
	v_mul_f32_e32 v146, v43, v143
	v_cvt_pk_bf16_f32 v142, v142, v146
	v_mul_f32_e32 v146, v44, v143
	v_mul_f32_e32 v143, v45, v143
	v_cvt_pk_bf16_f32 v143, v146, v143
	v_cndmask_b32_e64 v146, 0, 1, s[62:63]
	v_cmp_ne_u32_e64 s[2:3], 1, v146
	s_andn2_b64 vcc, exec, s[62:63]
	ds_write_b64 v196, v[142:143]
	s_cbranch_vccnz .LBB0_126
	v_mov_b32_e32 v139, v204

.LBB0_154:
	s_mul_i32 s59, s59, s55
	s_sub_i32 s2, s47, s59
	s_lshl_b32 s2, s2, 6
	v_mul_f32_e32 v144, v130, v139
	v_mul_f32_e32 v145, v131, v139
	v_cvt_pk_bf16_f32 v144, v144, v145
	v_mul_f32_e32 v145, v132, v139
	s_cmp_eq_u64 s[52:53], 0
	v_mul_f32_e32 v139, v133, v139
	v_cvt_pk_bf16_f32 v145, v145, v139
	ds_write_b64 v196, v[144:145] offset:8640
	s_cselect_b32 s84, 1, 2
	s_cbranch_scc1 .LBB0_45
	v_lshlrev_b32_e32 v139, 16, v142
	v_and_b32_e32 v142, 0xffff0000, v142
	v_lshlrev_b32_e32 v202, 16, v146
	v_and_b32_e32 v146, 0xffff0000, v146
	v_lshlrev_b32_e32 v196, 16, v143
	v_and_b32_e32 v143, 0xffff0000, v143
	v_max3_f32 v142, |v142|, 0, |v146|
	v_lshlrev_b32_e32 v146, 16, v147
	v_and_b32_e32 v147, 0xffff0000, v147
	v_max3_f32 v139, |v139|, 0, |v202|
	v_max3_f32 v143, |v143|, 0, |v147|
	v_lshlrev_b32_e32 v147, 16, v148
	v_lshlrev_b32_e32 v202, 16, v150
	v_and_b32_e32 v148, 0xffff0000, v148
	v_max3_f32 v139, v139, |v147|, |v202|
	v_and_b32_e32 v147, 0xffff0000, v150
	v_max3_f32 v146, |v196|, 0, |v146|
	v_lshlrev_b32_e32 v196, 16, v149
	v_max3_f32 v142, v142, |v148|, |v147|
	v_lshlrev_b32_e32 v147, 16, v151
	v_and_b32_e32 v149, 0xffff0000, v149
	v_max3_f32 v146, v146, |v196|, |v147|
	v_and_b32_e32 v147, 0xffff0000, v151
	v_max3_f32 v143, v143, |v149|, |v147|
	v_lshlrev_b32_e32 v147, 16, v152
	v_lshlrev_b32_e32 v151, 16, v154
	v_and_b32_e32 v148, 0xffff0000, v152
	v_max3_f32 v139, v139, |v147|, |v151|
	v_and_b32_e32 v147, 0xffff0000, v154
	v_lshlrev_b32_e32 v149, 16, v153
	v_max3_f32 v142, v142, |v148|, |v147|
	v_lshlrev_b32_e32 v147, 16, v155
	v_and_b32_e32 v150, 0xffff0000, v153
	v_max3_f32 v146, v146, |v149|, |v147|
	v_and_b32_e32 v147, 0xffff0000, v155
	v_max3_f32 v143, v143, |v150|, |v147|
	v_lshlrev_b32_e32 v147, 16, v156
	v_lshlrev_b32_e32 v151, 16, v158
	v_and_b32_e32 v148, 0xffff0000, v156
	v_max3_f32 v139, v139, |v147|, |v151|
	v_and_b32_e32 v147, 0xffff0000, v158
	v_lshlrev_b32_e32 v149, 16, v157
	v_max3_f32 v142, v142, |v148|, |v147|
	v_lshlrev_b32_e32 v147, 16, v159
	v_and_b32_e32 v150, 0xffff0000, v157
	v_max3_f32 v146, v146, |v149|, |v147|
	v_and_b32_e32 v147, 0xffff0000, v159
	v_max3_f32 v143, v143, |v150|, |v147|
	v_lshlrev_b32_e32 v147, 16, v160
	v_lshlrev_b32_e32 v151, 16, v162
	v_and_b32_e32 v148, 0xffff0000, v160
	v_max3_f32 v139, v139, |v147|, |v151|
	v_and_b32_e32 v147, 0xffff0000, v162
	v_lshlrev_b32_e32 v149, 16, v161
	v_max3_f32 v142, v142, |v148|, |v147|
	v_lshlrev_b32_e32 v147, 16, v163
	v_and_b32_e32 v150, 0xffff0000, v161
	v_max3_f32 v146, v146, |v149|, |v147|
	v_and_b32_e32 v147, 0xffff0000, v163
	v_max3_f32 v143, v143, |v150|, |v147|
	v_lshlrev_b32_e32 v147, 16, v164
	v_lshlrev_b32_e32 v151, 16, v166
	v_and_b32_e32 v148, 0xffff0000, v164
	v_max3_f32 v139, v139, |v147|, |v151|
	v_and_b32_e32 v147, 0xffff0000, v166
	v_lshlrev_b32_e32 v149, 16, v165
	v_max3_f32 v142, v142, |v148|, |v147|
	v_lshlrev_b32_e32 v147, 16, v167
	v_and_b32_e32 v150, 0xffff0000, v165
	v_max3_f32 v146, v146, |v149|, |v147|
	v_and_b32_e32 v147, 0xffff0000, v167
	v_max3_f32 v143, v143, |v150|, |v147|
	v_lshlrev_b32_e32 v147, 16, v168
	v_lshlrev_b32_e32 v151, 16, v170
	v_and_b32_e32 v148, 0xffff0000, v168
	v_max3_f32 v139, v139, |v147|, |v151|
	v_and_b32_e32 v147, 0xffff0000, v170
	v_lshlrev_b32_e32 v149, 16, v169
	v_max3_f32 v142, v142, |v148|, |v147|
	v_lshlrev_b32_e32 v147, 16, v171
	v_and_b32_e32 v150, 0xffff0000, v169
	v_max3_f32 v146, v146, |v149|, |v147|
	v_and_b32_e32 v147, 0xffff0000, v171
	v_max3_f32 v143, v143, |v150|, |v147|
	v_and_b32_e32 v150, 0xffff0000, v173
	v_and_b32_e32 v151, 0xffff0000, v145
	v_lshlrev_b32_e32 v147, 16, v172
	v_max3_f32 v150, v143, |v150|, |v151|
	v_lshlrev_b32_e32 v143, 16, v144
	v_max3_f32 v139, v139, |v147|, |v143|
	v_and_b32_e32 v147, 64, v195
	v_xor_b32_e32 v143, 16, v195
	v_add_u32_e32 v147, 64, v147
	v_cmp_lt_i32_e32 vcc, v143, v147
	v_and_b32_e32 v148, 0xffff0000, v172
	v_and_b32_e32 v144, 0xffff0000, v144
	v_cndmask_b32_e32 v143, v195, v143, vcc
	v_lshlrev_b32_e32 v151, 2, v143
	ds_bpermute_b32 v143, v151, v139
	v_lshlrev_b32_e32 v149, 16, v173
	v_lshlrev_b32_e32 v145, 16, v145
	v_max3_f32 v144, v142, |v148|, |v144|
	v_max3_f32 v145, v146, |v149|, |v145|
	s_waitcnt lgkmcnt(0)
	v_max_f32_e32 v142, v143, v143
	v_max_f32_e32 v139, v139, v142
	v_xor_b32_e32 v142, 32, v195
	ds_bpermute_b32 v143, v151, v144
	v_cmp_lt_i32_e32 vcc, v142, v147
	ds_bpermute_b32 v146, v151, v145
	ds_bpermute_b32 v147, v151, v150
	v_cndmask_b32_e32 v142, v195, v142, vcc
	s_waitcnt lgkmcnt(2)
	v_max_f32_e32 v143, v143, v143
	v_lshlrev_b32_e32 v148, 2, v142
	s_waitcnt lgkmcnt(1)
	v_max_f32_e32 v146, v146, v146
	s_waitcnt lgkmcnt(0)
	v_max_f32_e32 v147, v147, v147
	v_max_f32_e32 v143, v144, v143
	v_max_f32_e32 v145, v145, v146
	v_max_f32_e32 v147, v150, v147
	ds_bpermute_b32 v142, v148, v139
	ds_bpermute_b32 v144, v148, v143
	ds_bpermute_b32 v146, v148, v145
	ds_bpermute_b32 v148, v148, v147
	s_and_saveexec_b64 s[62:63], s[0:1]
	s_cbranch_execz .LBB0_44
	s_ashr_i32 s3, s2, 31
	s_lshl_b64 s[78:79], s[2:3], 2
	s_waitcnt lgkmcnt(3)
	v_max_f32_e32 v142, v142, v142
	v_max_f32_e32 v139, v139, v139
	s_add_u32 s78, s52, s78
	s_waitcnt lgkmcnt(0)
	v_max_f32_e32 v148, v148, v148
	v_max_f32_e32 v147, v147, v147
	v_max_f32_e32 v146, v146, v146
	v_max_f32_e32 v145, v145, v145
	v_max_f32_e32 v144, v144, v144
	v_max_f32_e32 v143, v143, v143
	v_max_f32_e32 v139, v139, v142
	s_addc_u32 s79, s53, s79
	v_lshlrev_b32_e32 v142, 2, v174
	v_max_f32_e32 v147, v147, v148
	v_max_f32_e32 v145, v145, v146
	v_max_f32_e32 v143, v143, v144
	global_atomic_umax v142, v139, s[78:79]
	global_atomic_umax v142, v143, s[78:79] offset:4
	global_atomic_umax v142, v145, s[78:79] offset:8
	global_atomic_umax v142, v147, s[78:79] offset:12
	s_branch .LBB0_44
